# prompt scan: one static priority raise for waves 4-7 before the scan loop (reset at the following grid barrier), on top of the VALU-free GEMM K-loops
# speedup vs baseline: 1.0091x; 1.0091x over previous
; __device__ __forceinline__ void seq_item(const Params& p, unsigned char* shm, int row0, int nchunks, int h, const float* S0, float* Sout) {
;     ...
;     f32x4 S[2];
; #pragma unroll
;     for (int q = 0; q < 2; ++q) S[q] = S0 ? *(const f32x4*)(S0 + (16 * (nv0 + q) + fr) * 64 + c0) : (f32x4){0.f, 0.f, 0.f, 0.f};
;     const int chi0 = (row0 >> 6) * 16 + h, last = nchunks - 1;
;     struct Stage { u32x4 g[4]; f32x4 gc; };
;     auto gload = [&](int ci, Stage& G) {
;         const size_t cb = (size_t)(chi0 + ci * 16) * 4096 + crow * 64 + cseg;
;         G.g[0] = *(const u32x4*)(p.W1G + cb); G.g[1] = *(const u32x4*)(p.BPG + cb); G.g[2] = *(const u32x4*)(p.U0G + cb); G.g[3] = *(const u32x4*)(p.VKG + cb);
;         G.gc = *(const f32x4*)(p.GCG + (size_t)(chi0 + ci * 16) * 64 + (tid & 15) * 4);
;     };
;     auto park = [&](int slot, const Stage& G) {
;         bf16_t* d = ring + slot * SLOT;
; #pragma unroll
;         for (int a = 0; a < 4; ++a) *(u32x4*)(d + a * 64 * LD + crow * LD + cseg) = G.g[a];
;         if (tid < 16) *(f32x4*)((float*)(d + 4 * 64 * LD) + tid * 4) = G.gc;
;     ...
;     Stage A, B;
;     gload(0, A); gload(min(1, last), B);
;     park(0, A); park(1, B);
;     gload(min(2, last), A);
.LBB0_431:
	s_andn2_b64 vcc, exec, s[2:3]
	s_cbranch_vccnz .LBB0_443
	s_lshl_b32 s2, s40, 9
	s_and_b32 s23, s2, 0xffffe000
	s_and_b32 s20, s40, 15
	s_ashr_i32 s21, s23, 2
	s_or_b32 s6, s21, s20
	s_ashr_i32 s7, s6, 31
	s_load_dwordx8 s[12:19], s[0:1], 0x108
	s_load_dwordx2 s[90:91], s[0:1], 0xb8
	s_load_dwordx2 s[92:93], s[0:1], 0x100
	v_readfirstlane_b32 s94, v133
	s_nop 3
	s_lshr_b32 s94, s94, 8
	s_cmp_eq_u32 s94, 0
	s_cbranch_scc1 .Lscan_prio0
	s_setprio 1
.Lscan_prio0:
	s_lshl_b64 s[2:3], s[6:7], 12
	s_waitcnt vmcnt(2)
	v_lshlrev_b32_e32 v20, 6, v164
	v_mov_b32_e32 v21, 0
	v_and_b32_e32 v22, 56, v131
	v_lshl_add_u64 v[0:1], s[2:3], 0, v[20:21]
	v_or_b32_e32 v0, v0, v22
	v_lshlrev_b64 v[0:1], 1, v[0:1]
	s_waitcnt lgkmcnt(0)
	v_lshl_add_u64 v[2:3], s[12:13], 0, v[0:1]
	s_or_b32 s2, s6, 16
	global_load_dwordx4 v[24:27], v[2:3], off
	v_lshl_add_u64 v[2:3], s[14:15], 0, v[0:1]
	s_ashr_i32 s3, s2, 31
	global_load_dwordx4 v[28:31], v[2:3], off
	v_lshl_add_u64 v[2:3], s[16:17], 0, v[0:1]
	v_lshl_add_u64 v[0:1], s[18:19], 0, v[0:1]
	s_load_dwordx2 s[10:11], s[0:1], 0x130
	s_lshl_b64 s[4:5], s[2:3], 12
	global_load_dwordx4 v[36:39], v[0:1], off
	v_lshl_add_u64 v[0:1], s[4:5], 0, v[20:21]
	v_or_b32_e32 v0, v0, v22
	v_lshlrev_b64 v[0:1], 1, v[0:1]
	global_load_dwordx4 v[32:35], v[2:3], off
	v_lshl_add_u64 v[2:3], s[12:13], 0, v[0:1]
	s_lshl_b64 s[2:3], s[2:3], 8
	global_load_dwordx4 v[4:7], v[2:3], off
	v_lshl_add_u64 v[2:3], s[14:15], 0, v[0:1]
	s_waitcnt lgkmcnt(0)
	s_add_u32 s2, s10, s2
	global_load_dwordx4 v[12:15], v[2:3], off
	v_lshl_add_u64 v[2:3], s[16:17], 0, v[0:1]
	s_addc_u32 s3, s11, s3
	global_load_dwordx4 v[8:11], v[2:3], off
	v_lshl_add_u64 v[40:41], s[18:19], 0, v[0:1]
	global_load_dwordx4 v[0:3], v120, s[2:3]
	global_load_dwordx4 v[16:19], v[40:41], off
	s_load_dwordx2 s[2:3], s[0:1], 0xb0
	v_mul_u32_u24_e32 v23, 0x48, v164
	v_lshlrev_b32_e32 v51, 1, v23
	v_lshlrev_b32_e32 v48, 1, v22
	v_cmp_gt_u32_e64 s[8:9], 16, v133
	v_add3_u32 v60, 0, v51, v48
	v_lshl_add_u32 v23, v134, 2, 0
	s_waitcnt vmcnt(8)
	ds_write_b128 v60, v[24:27] offset:18432
	s_waitcnt vmcnt(7)
	ds_write_b128 v60, v[28:31] offset:27648
	s_waitcnt vmcnt(5)
	ds_write_b128 v60, v[32:35] offset:36864
	ds_write_b128 v60, v[36:39] offset:46080
	s_and_saveexec_b64 s[4:5], s[8:9]
	s_cbranch_execz .LBB0_434
	s_lshl_b64 s[24:25], s[6:7], 8
	s_add_u32 s24, s10, s24
	s_addc_u32 s25, s11, s25
	global_load_dwordx4 v[24:27], v120, s[24:25]
	s_waitcnt vmcnt(0)
	ds_write_b128 v23, v[24:27] offset:55296

; #define LDS_BARRIER() do { asm volatile("s_waitcnt lgkmcnt(0)" ::: "memory"); __builtin_amdgcn_s_barrier(); asm volatile("" ::: "memory"); } while (0)
; __device__ __forceinline__ unsigned xb_add(unsigned* p, unsigned v) { return __hip_atomic_fetch_add(p, v, __ATOMIC_RELAXED, __HIP_MEMORY_SCOPE_AGENT); }
; __device__ __forceinline__ void seq_item(const Params& p, unsigned char* shm, int row0, int nchunks, int h, const float* S0, float* Sout) {
;     ...
;     LDS_BARRIER();
; #pragma unroll
;     for (int q = 0; q < 2; ++q) *(f32x4*)(Sout + (16 * (nv0 + q) + fr) * 64 + c0) = S[q];
; __device__ __forceinline__ void xcd_barrier(XcdBarrier& b) {
;     asm volatile("s_waitcnt vmcnt(0)" ::: "memory");
;     __syncthreads();
;     if (threadIdx.x == 0) {
;         unsigned* bar = b.bar;
;         __builtin_amdgcn_s_waitcnt(0);
;         if (b.nloc == 0u) xcd_barrier_complete(bar, b.x, b.nloc, b.nx);
;         const unsigned nloc = b.nloc, nx = b.nx;
;         const unsigned old = xb_add(&bar[XB_XSUB(b.x)], 1u);
;         const unsigned gen = old / nloc;
;         if (old + 1u == (gen + 1u) * nloc) {
.LBB0_442:
	s_ashr_i32 s41, s40, 31
	s_lshl_b64 s[4:5], s[40:41], 14
	s_add_u32 s2, s2, s4
	s_addc_u32 s3, s3, s5
	s_waitcnt vmcnt(5)
	v_lshlrev_b32_e32 v0, 2, v50
	v_mov_b32_e32 v1, 0
	v_lshl_add_u64 v[2:3], s[2:3], 0, v[0:1]
	v_lshlrev_b32_e32 v0, 8, v161
	v_lshl_or_b32 v0, v61, 12, v0
	v_lshl_add_u64 v[0:1], v[2:3], 0, v[0:1]
	v_add_co_u32_e32 v2, vcc, 0x11000000, v0
	s_waitcnt lgkmcnt(0)
	s_barrier
	s_nop 0
	v_addc_co_u32_e32 v3, vcc, 0, v1, vcc
	v_add_co_u32_e32 v0, vcc, 0x11001000, v0
	global_store_dwordx4 v[2:3], v[24:27], off
	s_nop 0
	v_addc_co_u32_e32 v1, vcc, 0, v1, vcc
	global_store_dwordx4 v[0:1], v[20:23], off
.LBB0_443:
	s_setprio 0
	s_waitcnt vmcnt(0)
	s_barrier
	s_mov_b64 s[2:3], exec
	v_readlane_b32 s4, v244, 1
	v_readlane_b32 s5, v244, 2
	s_and_b64 s[4:5], s[2:3], s[4:5]
	s_mov_b64 exec, s[4:5]
	s_cbranch_execz .LBB0_496
	v_cmp_eq_u32_e32 vcc, 0, v130
	s_waitcnt vmcnt(0) expcnt(0) lgkmcnt(0)
	s_and_saveexec_b64 s[4:5], vcc
	s_cbranch_execz .LBB0_459
	v_readlane_b32 s6, v244, 0
	s_mul_i32 s20, s39, s6
	s_add_u32 s6, s36, 0x1000
	s_addc_u32 s7, s37, 0
	s_add_u32 s8, s36, 0x1100
	s_addc_u32 s9, s37, 0
	s_add_u32 s10, s36, 0x1200
	s_addc_u32 s11, s37, 0
	s_add_u32 s12, s36, 0x1300
	s_mul_i32 s20, s20, s38
	s_addc_u32 s13, s37, 0
	s_mov_b32 s21, 1
	v_mov_b32_e32 v16, 0
	s_branch .LBB0_447
